# grid barrier: L1/L2 invalidate issued at arrival (overlaps the arrival atomic and the wait) instead of after the release
# speedup vs baseline: 1.0212x; 1.0212x over previous
.LBB0_311:
	s_waitcnt lgkmcnt(0)
	buffer_inv sc1
	v_readlane_b32 s16, v254, 56
	v_readlane_b32 s4, v252, 14
	v_readlane_b32 s5, v252, 15
	v_mov_b32_e32 v4, 1
	v_mov_b32_e32 v6, s16
	ds_read_b32 v5, v6 offset:8
	s_nop 3
	global_atomic_add v4, v3, v4, s[4:5] sc0
	s_waitcnt vmcnt(0) lgkmcnt(0)
	v_add_u32_e32 v5, 1, v5
	v_mul_lo_u32 v1, v5, v2
	v_mul_lo_u32 v8, v5, v0
	v_add_u32_e32 v4, 1, v4
	ds_write_b32 v6, v5 offset:8
	v_readlane_b32 s4, v252, 18
	v_readlane_b32 s5, v252, 19
	v_readfirstlane_b32 s20, v1
	v_readfirstlane_b32 s21, v4
	v_readfirstlane_b32 s17, v8
	s_cmp_lg_u32 s21, s20
	s_cbranch_scc1 .Lxb0_poll
	buffer_wbl2 sc1
	s_waitcnt vmcnt(0)
.Lxb0_nowb:
	v_mov_b32_e32 v4, 1
	global_atomic_add v3, v4, s[4:5]

.Lxb0_done:
.Lxb0_noinv:
	s_waitcnt vmcnt(0) lgkmcnt(0)

.Lxb8_done:
.Lxb8_noinv:
	s_waitcnt vmcnt(0) lgkmcnt(0)
	s_mov_b64 s[4:5], 0
	s_getpc_b64 s[98:99]
